# P0: waves 4-7 run the row loop before the weight transposes (roles staggered between the two waves of each SIMD)
# speedup vs baseline: 1.0018x; 1.0018x over previous
; #define LAS __attribute__((address_space(3)))
; __device__ __forceinline__ void p0_prologue(const Args& a, LAS unsigned char* lds, int gw, int NGW, int lane, int wave) {
;     unsigned char* ws = a.ws;
;     LAS float* scr = (LAS float*)(lds + wave * 16384);
;     bf16_t* WinT = (bf16_t*)(ws + WS_WIN); bf16_t* WoutT = (bf16_t*)(ws + WS_WOUT); bf16_t* WupT = (bf16_t*)(ws + WS_WUP); bf16_t* WdownT = (bf16_t*)(ws + WS_WDOWN);
;     constexpr int I_IN = 16 * 64, I_OUT = 16 * 32, I_UP = 16 * 176, I_DOWN = 44 * 32, NIT = I_IN + I_OUT + I_UP + I_DOWN;
;     for (int it = gw; it < NIT; it += NGW) {
;         int r = it;
;         if (r < I_IN) { const int kb = r / 64, nb = r % 64; const int dst = nb * 32; const int src = dst < 1536 ? dst : dst + 8;
;             transpose_item(a.in[I_WIN], 2056, 1024, WinT, a.in[I_PREMIX], scr, kb * 64, src, dst, lane); continue; }
; __global__ void __launch_bounds__(512, 2) fwd_kernel(Args a) {
;     ...
;     const int tid = threadIdx.x, lane = tid & 63, wave = __builtin_amdgcn_readfirstlane(tid >> 6);
;     const int G = gridDim.x, bx = blockIdx.x;
;     const int gw = bx * 8 + wave, NGW = G * 8;
;     unsigned char* ws = a.ws;
;     ...
;     cg::grid_group grid = cg::this_grid();
;     volatile LAS unsigned* bst = (volatile LAS unsigned*)(lds + LDS_BYTES - 16);
;     if (tid < 4) bst[tid] = 0u;
;     __syncthreads();
;     XcdBarrier xbar = xcd_barrier_post((unsigned*)(ws + WS_BAR), bst);
;     ...
;     if (IN(0)) { p0_prologue(a, lds, gw, NGW, lane, wave); }
.LBB0_5:
	s_or_b64 exec, exec, s[2:3]
	s_load_dwordx16 s[4:19], s[0:1], 0x0
	s_lshl_b32 s97, s38, 3
	v_and_b32_e32 v176, 63, v177
	s_waitcnt lgkmcnt(0)
	v_writelane_b32 v254, s4, 7
	s_nop 1
	v_writelane_b32 v254, s5, 8
	v_writelane_b32 v254, s6, 9
	v_writelane_b32 v254, s7, 10
	v_writelane_b32 v254, s8, 11
	v_writelane_b32 v254, s9, 12
	v_writelane_b32 v254, s10, 13
	v_writelane_b32 v254, s11, 14
	v_writelane_b32 v254, s12, 15
	v_writelane_b32 v254, s13, 16
	v_writelane_b32 v254, s14, 17
	v_writelane_b32 v254, s15, 18
	v_writelane_b32 v254, s16, 19
	v_writelane_b32 v254, s17, 20
	v_writelane_b32 v254, s18, 21
	v_writelane_b32 v254, s19, 22
	s_load_dwordx16 s[68:83], s[0:1], 0x40
	s_load_dwordx16 s[4:19], s[0:1], 0xc0
	s_waitcnt lgkmcnt(0)
	v_writelane_b32 v254, s4, 23
	s_nop 1
	v_writelane_b32 v254, s5, 24
	v_writelane_b32 v254, s6, 25
	v_writelane_b32 v254, s7, 26
	v_writelane_b32 v254, s8, 27
	v_writelane_b32 v254, s9, 28
	v_writelane_b32 v254, s10, 29
	v_writelane_b32 v254, s11, 30
	v_writelane_b32 v254, s12, 31
	v_writelane_b32 v254, s13, 32
	v_writelane_b32 v254, s14, 33
	v_writelane_b32 v254, s15, 34
	v_writelane_b32 v254, s16, 35
	v_writelane_b32 v254, s17, 36
	v_writelane_b32 v254, s18, 37
	v_writelane_b32 v254, s19, 38
	s_nop 0
	v_readlane_b32 s2, v254, 1
	s_lshr_b32 s3, s2, 6
	s_lshl_b32 s2, s96, 3
	s_add_i32 s2, s3, s2
	s_cmp_lt_i32 s90, 1
	v_writelane_b32 v254, s3, 39
	s_cselect_b64 s[94:95], -1, 0
	s_cmp_gt_i32 s91, 0
	v_writelane_b32 v254, s2, 40
	s_cselect_b64 s[2:3], -1, 0
	s_and_b64 s[2:3], s[94:95], s[2:3]
	v_writelane_b32 v254, s38, 41
	s_andn2_b64 vcc, exec, s[2:3]
	s_nop 0
	v_writelane_b32 v254, s39, 42
	s_cbranch_vccnz .LBB0_80
	v_readlane_b32 s2, v254, 39
	s_cmp_gt_u32 s2, 3
	s_cbranch_scc1 .Lp0_rows_entry
.Lp0_tr_entry:
	v_readlane_b32 s2, v254, 40
	s_cmpk_gt_i32 s2, 0x167f
	s_cbranch_scc1 .LBB0_61
	v_and_b32_e32 v1, 31, v177
	v_lshlrev_b32_e32 v24, 2, v1
	v_lshlrev_b32_e32 v1, 3, v177
	s_load_dwordx16 s[16:31], s[0:1], 0xc0
	v_and_b32_e32 v1, 56, v1
	s_load_dwordx16 s[40:55], s[0:1], 0x0
	v_readlane_b32 s2, v254, 39
	v_lshrrev_b32_e32 v2, 5, v176
	v_lshlrev_b32_e32 v6, 1, v1
	v_mov_b32_e32 v7, 0
	s_lshl_b32 s4, s2, 14
	v_lshl_add_u64 v[14:15], s[88:89], 0, v[6:7]
	v_mul_u32_u24_e32 v6, 0x84, v2
	s_add_i32 s6, s4, 0
	v_lshrrev_b32_e32 v3, 3, v176
	s_mov_b64 s[2:3], 0x1c00000
	v_or_b32_e32 v6, s4, v6
	v_mul_u32_u24_e32 v5, 0x84, v1
	v_lshl_add_u64 v[8:9], v[14:15], 0, s[2:3]
	v_lshlrev_b32_e32 v1, 2, v3
	s_mov_b64 s[2:3], 0x1000000
	v_mov_b32_e32 v25, v7
	s_waitcnt lgkmcnt(0)
	s_cmp_lg_u64 s[22:23], 0
	v_add3_u32 v49, v6, v24, 0
	v_mul_u32_u24_e32 v6, 0x5800, v2
	v_add_u32_e32 v4, s6, v24
	v_add3_u32 v5, s6, v5, v1
	v_lshl_add_u64 v[10:11], v[14:15], 0, s[2:3]
	s_mov_b64 s[2:3], 0xe00000
	v_lshl_add_u64 v[16:17], s[30:31], 0, v[24:25]
	v_lshl_add_u64 v[18:19], s[18:19], 0, v[24:25]
	v_lshl_add_u64 v[20:21], s[68:69], 0, v[24:25]
	s_cselect_b64 s[6:7], -1, 0
	s_cmp_lg_u64 s[54:55], 0
	v_lshl_add_u64 v[22:23], s[24:25], 0, v[24:25]
	v_or_b32_e32 v24, v6, v24
	v_lshlrev_b32_e32 v6, 2, v2
	v_lshl_add_u64 v[12:13], v[14:15], 0, s[2:3]
	s_mov_b64 s[2:3], 0xa00000
	s_cselect_b64 s[8:9], -1, 0
	v_mul_hi_u32_u24_e32 v25, 0x5800, v2
	v_lshl_add_u64 v[26:27], s[22:23], 0, v[6:7]
	s_add_u32 s10, s54, 56
	s_mov_b32 s5, 0
	s_movk_i32 s14, 0x84
	v_or_b32_e32 v46, 8, v3
	v_or_b32_e32 v47, 16, v3
	v_or_b32_e32 v48, 24, v3
	v_lshl_add_u64 v[14:15], v[14:15], 0, s[2:3]
	v_mov_b32_e32 v1, v2
	v_or_b32_e32 v50, 14, v2
	v_lshl_add_u64 v[24:25], s[24:25], 0, v[24:25]
	v_or_b32_e32 v51, 12, v2
	v_lshl_add_u64 v[26:27], v[26:27], 0, 56
	v_or_b32_e32 v52, 10, v2
	v_or_b32_e32 v53, 8, v2
	v_or_b32_e32 v54, 6, v2
	v_or_b32_e32 v55, 4, v2
	v_or_b32_e32 v56, 2, v2
	s_addc_u32 s11, s55, 0
	s_movk_i32 s15, 0x2020
	v_readlane_b32 s16, v254, 40
	s_branch .LBB0_10

; __device__ __forceinline__ void p0_prologue(const Args& a, LAS unsigned char* lds, int gw, int NGW, int lane, int wave) {
;     ...
;     for (int it = gw; it < NIT; it += NGW) {
;         int r = it;
;         if (r < I_IN) { const int kb = r / 64, nb = r % 64; const int dst = nb * 32; const int src = dst < 1536 ? dst : dst + 8;
;             transpose_item(a.in[I_WIN], 2056, 1024, WinT, a.in[I_PREMIX], scr, kb * 64, src, dst, lane); continue; }
;         r -= I_IN;
;         if (r < I_OUT) { const int kb = r / 32, nb = r % 32; transpose_item(a.in[I_WOUT], 1024, 1024, WoutT, nullptr, scr, kb * 64, nb * 32, nb * 32, lane); continue; }
;         r -= I_OUT;
;         if (r < I_UP) { const int kb = r / 176, nb = r % 176; const int dst = nb * 32; const int pn = dst >> 8, i = dst & 255; const int src = i < 128 ? pn * 128 + i : DFF + pn * 128 + (i - 128);
;             transpose_item(a.in[I_WUP], NUP, 1024, WupT, a.in[I_PREFFN], scr, kb * 64, src, dst, lane); continue; }
;         r -= I_UP;
;         { const int kb = r / 32, nb = r % 32; transpose_item(a.in[I_WDOWN], 1024, DFF, WdownT, nullptr, scr, kb * 64, nb * 32, nb * 32, lane); }
;     }
;     { float* s2 = (float*)(ws + WS_SUMSQ2); float* s4 = (float*)(ws + WS_SUMSQ4);
;       for (int i = gw * 64 + lane; i < R; i += NGW * 64) { s2[i] = 0.f; s4[i] = 0.f; } }
.LBB0_61:
	v_readlane_b32 s2, v254, 39
	s_cmp_gt_u32 s2, 3
	s_cbranch_scc1 .LBB0_80

; __device__ __forceinline__ unsigned pk2(float lo, float hi) { f32x2 v; v.x = lo; v.y = hi; return __builtin_bit_cast(unsigned, __builtin_convertvector(v, hwbf2)); }
; __device__ __forceinline__ void p0_prologue(const Args& a, LAS unsigned char* lds, int gw, int NGW, int lane, int wave) {
;     ...
;     for (int it = gw; it < NIT; it += NGW) {
;     ...
;     for (int row0 = 2 * gw; row0 < R; row0 += 2 * NGW) {
;         f32x4 vv[2][4];
; #pragma unroll
;         for (int rr = 0; rr < 2; ++rr) { const int row = row0 + rr;
;             const float* xr = row < RP ? a.in[I_XP] + (size_t)row * DM : a.in[I_XS] + (size_t)(row - RP) * DM;
; #pragma unroll
;             for (int q = 0; q < 4; ++q) vv[rr][q] = *(const f32x4*)(xr + q * 256 + lane * 4); }
; #pragma unroll
;         for (int rr = 0; rr < 2; ++rr) { const int row = row0 + rr;
;             float ss = 0.f;
; #pragma unroll
;             for (int q = 0; q < 4; ++q) { const f32x4 v = vv[rr][q]; ss += (v[0] * v[0] + v[1] * v[1]) + (v[2] * v[2] + v[3] * v[3]); }
;             ss = wave_sum(ss);
;             const float rs = 1.f / sqrtf(ss * (1.f / DM) + EPS);
; #pragma unroll
;             for (int q = 0; q < 4; ++q) { const f32x4 v = vv[rr][q]; u32x2 w; w.x = pk2(v[0], v[1]); w.y = pk2(v[2], v[3]); *(u32x2*)(xb + (size_t)row * DM + q * 256 + lane * 4) = w; }
;             float myd = 0.f;
; #pragma unroll
;             for (int j = 0; j < 8; ++j) { float d = 0.f;
; #pragma unroll
;                 for (int q = 0; q < 4; ++q)
; #pragma unroll
;                     for (int e = 0; e < 4; ++e) d += vv[rr][q][e] * wd[j][q * 4 + e];
;                 d = wave_sum(d);
;                 if (lane == j) myd = d; }
;             if (lane < 8) { const float xx = myd * rs + dtb[lane]; dtv[(size_t)row * 8 + lane] = xx > 20.f ? xx : log1pf(expf(xx)); }
;             if (lane == 0) rstd1[row] = rs; }
;     }
.LBB0_79:
	s_load_dwordx2 s[38:39], s[0:1], 0x120
	v_readlane_b32 s2, v254, 39
	s_cmp_gt_u32 s2, 3
	s_cbranch_scc0 .LBB0_80
	s_load_dwordx2 s[68:69], s[0:1], 0x40
	s_waitcnt lgkmcnt(0)
	s_branch .Lp0_tr_entry
